# P4 epilogue: second-half residual loads issued before the first-half stores (results kept in the residual registers), counted wait instead of a full drain
# speedup vs baseline: 1.0011x; 1.0011x over previous
; __device__ __forceinline__ void gemm_epi(const Params& p, int l, int kind, const GUnit& u, f32x4 (&acc)[2][2][4][2]) {
;     ...
;   if (kind == 4) {
;     const int col0 = u.pn * 256 + wc * 32 + 4 * fq;
;     const float* xbase = (l == 0) ? (u.pm < 256 ? p.xp : p.xs - (long)NP * 1024) : p.out;
; #pragma unroll
;     for (int ai = 0; ai < 2; ++ai) {
;       f32x4 xv[4][2][2];
; #pragma unroll
;       for (int m = 0; m < 4; ++m) {
;         const float* xr = xbase + (long)(row0 + ai * 128 + m * 16) * 1024 + col0;
; #pragma unroll
;         for (int bj = 0; bj < 2; ++bj)
; #pragma unroll
;           for (int n = 0; n < 2; ++n) xv[m][bj][n] = *reinterpret_cast<const f32x4*>(xr + bj * 128 + n * 16);
;       }
.Lal4_a:
	v_mov_b32_e32 v134, v188
	s_lshl_b32 s5, s25, 8
	v_readfirstlane_b32 s1, v134
	s_ashr_i32 s12, s1, 2
	s_andn2_b32 s12, s12, 63
	s_lshr_b32 s1, s1, 1
	s_add_i32 s12, s12, s5
	s_lshl_b32 s5, s26, 8
	s_and_b32 s1, s1, 0x60
	s_or_b32 s1, s1, s5
	v_readlane_b32 s36, v248, 20
	v_and_or_b32 v138, v134, 15, s12
	v_lshrrev_b32_e32 v134, 2, v134
	s_cmpk_lt_i32 s25, 0x100
	v_readlane_b32 s37, v248, 21
	v_readlane_b32 s38, v248, 22
	v_readlane_b32 s39, v248, 23
	v_readlane_b32 s40, v248, 24
	v_readlane_b32 s41, v248, 25
	v_readlane_b32 s42, v248, 26
	v_readlane_b32 s43, v248, 27
	v_readlane_b32 s12, v247, 48
	v_and_or_b32 v134, v134, 12, s1
	s_cselect_b32 s1, s36, s81
	s_cselect_b32 s5, s37, s88
	v_readlane_b32 s13, v247, 49
	v_readlane_b32 s36, v248, 49
	s_and_b64 s[12:13], s[12:13], exec
	v_readlane_b32 s37, v248, 50
	v_ashrrev_i32_e32 v135, 31, v134
	s_cselect_b32 s13, s5, s37
	s_cselect_b32 s12, s1, s36
	v_lshlrev_b64 v[134:135], 2, v[134:135]
	v_ashrrev_i32_e32 v139, 31, v138
	v_lshl_add_u64 v[136:137], s[12:13], 0, v[134:135]
	v_lshlrev_b64 v[138:139], 12, v[138:139]
	s_mov_b64 s[12:13], 0x10000
	v_lshl_add_u64 v[186:187], v[138:139], 0, s[12:13]
	s_mov_b64 s[12:13], 0x20000
	v_lshl_add_u64 v[230:231], v[138:139], 0, s[12:13]
	s_mov_b64 s[12:13], 0x30000
	v_lshl_add_u64 v[154:155], v[136:137], 0, v[138:139]
	v_lshl_add_u64 v[232:233], v[138:139], 0, s[12:13]
	global_load_dwordx4 v[142:145], v[154:155], off
	global_load_dwordx4 v[146:149], v[154:155], off offset:64
	global_load_dwordx4 v[150:153], v[154:155], off offset:512
	s_nop 0
	global_load_dwordx4 v[154:157], v[154:155], off offset:576
	v_lshl_add_u64 v[170:171], v[136:137], 0, v[186:187]
	v_lshl_add_u64 v[200:201], v[136:137], 0, v[230:231]
	v_lshl_add_u64 v[226:227], v[136:137], 0, v[232:233]
	global_load_dwordx4 v[158:161], v[170:171], off
	global_load_dwordx4 v[162:165], v[170:171], off offset:64
	global_load_dwordx4 v[166:169], v[170:171], off offset:512
	s_nop 0
	global_load_dwordx4 v[170:173], v[170:171], off offset:576
	s_nop 0
	global_load_dwordx4 v[174:177], v[200:201], off
	global_load_dwordx4 v[178:181], v[200:201], off offset:64
	global_load_dwordx4 v[182:185], v[200:201], off offset:512
	s_nop 0
	global_load_dwordx4 v[200:203], v[200:201], off offset:576
	s_nop 0
	global_load_dwordx4 v[204:207], v[226:227], off
	global_load_dwordx4 v[218:221], v[226:227], off offset:64
	global_load_dwordx4 v[222:225], v[226:227], off offset:512
	s_nop 0
	global_load_dwordx4 v[226:229], v[226:227], off offset:576
	v_lshl_add_u64 v[234:235], s[36:37], 0, v[138:139]
	v_lshl_add_u64 v[234:235], v[234:235], 0, v[134:135]
	v_lshl_add_u64 v[186:187], s[36:37], 0, v[186:187]
	v_lshl_add_u64 v[232:233], s[36:37], 0, v[232:233]
	v_lshl_add_u64 v[230:231], s[36:37], 0, v[230:231]
	v_lshl_add_u64 v[186:187], v[186:187], 0, v[134:135]
	v_lshl_add_u64 v[232:233], v[232:233], 0, v[134:135]
	v_readlane_b32 s38, v248, 51
	v_readlane_b32 s39, v248, 52
	v_readlane_b32 s40, v248, 53
	v_readlane_b32 s41, v248, 54
	v_readlane_b32 s42, v248, 55
	v_readlane_b32 s43, v248, 56
	v_readlane_b32 s44, v248, 57
	v_readlane_b32 s45, v248, 58
	v_readlane_b32 s46, v248, 59
	v_readlane_b32 s47, v248, 60
	v_readlane_b32 s48, v248, 61
	v_readlane_b32 s49, v248, 62
	v_readlane_b32 s50, v248, 63
	v_readlane_b32 s51, v247, 0
	v_lshl_add_u64 v[230:231], v[230:231], 0, v[134:135]
	s_waitcnt vmcnt(0)
; __device__ __forceinline__ void gemm_epi(const Params& p, int l, int kind, const GUnit& u, f32x4 (&acc)[2][2][4][2]) {
;     ...
;     for (int ai = 0; ai < 2; ++ai) {
;       f32x4 xv[4][2][2];
; #pragma unroll
;       for (int m = 0; m < 4; ++m) {
;         const float* xr = xbase + (long)(row0 + ai * 128 + m * 16) * 1024 + col0;
; #pragma unroll
;         for (int bj = 0; bj < 2; ++bj)
; #pragma unroll
;           for (int n = 0; n < 2; ++n) xv[m][bj][n] = *reinterpret_cast<const f32x4*>(xr + bj * 128 + n * 16);
;       }
; #pragma unroll
;       for (int m = 0; m < 4; ++m) {
;         float* yr = p.out + (long)(row0 + ai * 128 + m * 16) * 1024 + col0;
; #pragma unroll
;         for (int bj = 0; bj < 2; ++bj)
; #pragma unroll
;           for (int n = 0; n < 2; ++n) *reinterpret_cast<f32x4*>(yr + bj * 128 + n * 16) = xv[m][bj][n] + acc[ai][bj][m][n];
;       }
;       __builtin_amdgcn_sched_barrier(0);
;     }
	v_pk_add_f32 v[144:145], v[126:127], v[144:145]
	v_pk_add_f32 v[142:143], v[124:125], v[142:143]
	v_pk_add_f32 v[148:149], v[122:123], v[148:149]
	v_pk_add_f32 v[156:157], v[98:99], v[156:157]
	v_pk_add_f32 v[154:155], v[96:97], v[154:155]
	v_pk_add_f32 v[146:147], v[120:121], v[146:147]
	v_pk_add_f32 v[152:153], v[106:107], v[152:153]
	v_pk_add_f32 v[150:151], v[104:105], v[150:151]
	v_pk_add_f32 v[206:207], v[86:87], v[206:207]
	v_pk_add_f32 v[204:205], v[84:85], v[204:205]
	v_pk_add_f32 v[160:161], v[118:119], v[160:161]
	v_pk_add_f32 v[158:159], v[116:117], v[158:159]
	v_pk_add_f32 v[220:221], v[74:75], v[220:221]
	v_pk_add_f32 v[218:219], v[72:73], v[218:219]
	v_pk_add_f32 v[224:225], v[70:71], v[224:225]
	v_pk_add_f32 v[222:223], v[68:69], v[222:223]
	v_pk_add_f32 v[228:229], v[66:67], v[228:229]
	v_pk_add_f32 v[226:227], v[64:65], v[226:227]
	v_pk_add_f32 v[164:165], v[114:115], v[164:165]
	v_pk_add_f32 v[162:163], v[112:113], v[162:163]
	v_pk_add_f32 v[168:169], v[94:95], v[168:169]
	v_pk_add_f32 v[166:167], v[92:93], v[166:167]
	v_pk_add_f32 v[172:173], v[90:91], v[172:173]
	v_pk_add_f32 v[170:171], v[88:89], v[170:171]
	v_pk_add_f32 v[176:177], v[110:111], v[176:177]
	v_pk_add_f32 v[174:175], v[108:109], v[174:175]
	v_pk_add_f32 v[180:181], v[102:103], v[180:181]
	v_pk_add_f32 v[178:179], v[100:101], v[178:179]
	v_pk_add_f32 v[184:185], v[82:83], v[184:185]
	v_pk_add_f32 v[182:183], v[80:81], v[182:183]
	v_pk_add_f32 v[202:203], v[78:79], v[202:203]
	v_pk_add_f32 v[200:201], v[76:77], v[200:201]
	s_mov_b64 s[12:13], 0x80000
	v_lshl_add_u64 v[236:237], v[138:139], 0, s[12:13]
	s_mov_b64 s[12:13], 0x90000
	v_lshl_add_u64 v[238:239], v[138:139], 0, s[12:13]
	s_mov_b64 s[12:13], 0xa0000
	v_lshl_add_u64 v[240:241], v[138:139], 0, s[12:13]
	s_mov_b64 s[12:13], 0xb0000
	v_lshl_add_u64 v[138:139], v[138:139], 0, s[12:13]
	v_lshl_add_u64 v[76:77], v[136:137], 0, v[236:237]
	v_lshl_add_u64 v[92:93], v[136:137], 0, v[238:239]
	v_lshl_add_u64 v[108:109], v[136:137], 0, v[240:241]
	v_lshl_add_u64 v[124:125], v[136:137], 0, v[138:139]
	global_load_dwordx4 v[64:67], v[76:77], off
	global_load_dwordx4 v[68:71], v[76:77], off offset:64
	global_load_dwordx4 v[72:75], v[76:77], off offset:512
	s_nop 0
	global_load_dwordx4 v[76:79], v[76:77], off offset:576
	s_nop 0
	global_load_dwordx4 v[80:83], v[92:93], off
	global_load_dwordx4 v[84:87], v[92:93], off offset:64
	global_load_dwordx4 v[88:91], v[92:93], off offset:512
	s_nop 0
	global_load_dwordx4 v[92:95], v[92:93], off offset:576
	s_nop 0
	global_load_dwordx4 v[96:99], v[108:109], off
	global_load_dwordx4 v[100:103], v[108:109], off offset:64
	global_load_dwordx4 v[104:107], v[108:109], off offset:512
	s_nop 0
	global_load_dwordx4 v[108:111], v[108:109], off offset:576
	s_nop 0
	global_load_dwordx4 v[112:115], v[124:125], off
	global_load_dwordx4 v[116:119], v[124:125], off offset:64
	global_load_dwordx4 v[120:123], v[124:125], off offset:512
	s_nop 0
	global_load_dwordx4 v[124:127], v[124:125], off offset:576
	global_store_dwordx4 v[234:235], v[142:145], off
	global_store_dwordx4 v[234:235], v[146:149], off offset:64
	global_store_dwordx4 v[234:235], v[150:153], off offset:512
	global_store_dwordx4 v[234:235], v[154:157], off offset:576
	global_store_dwordx4 v[186:187], v[158:161], off
	global_store_dwordx4 v[186:187], v[162:165], off offset:64
	global_store_dwordx4 v[186:187], v[166:169], off offset:512
	global_store_dwordx4 v[186:187], v[170:173], off offset:576
	global_store_dwordx4 v[230:231], v[174:177], off
	global_store_dwordx4 v[230:231], v[178:181], off offset:64
	global_store_dwordx4 v[230:231], v[182:185], off offset:512
	global_store_dwordx4 v[230:231], v[200:203], off offset:576
	global_store_dwordx4 v[232:233], v[204:207], off
	global_store_dwordx4 v[232:233], v[218:221], off offset:64
	global_store_dwordx4 v[232:233], v[222:225], off offset:512
	global_store_dwordx4 v[232:233], v[226:229], off offset:576
	v_lshl_add_u64 v[136:137], s[36:37], 0, v[236:237]
	v_lshl_add_u64 v[142:143], s[36:37], 0, v[238:239]
	v_lshl_add_u64 v[144:145], s[36:37], 0, v[240:241]
	v_lshl_add_u64 v[138:139], s[36:37], 0, v[138:139]
	v_lshl_add_u64 v[136:137], v[136:137], 0, v[134:135]
	v_lshl_add_u64 v[142:143], v[142:143], 0, v[134:135]
	v_lshl_add_u64 v[144:145], v[144:145], 0, v[134:135]
	v_lshl_add_u64 v[134:135], v[138:139], 0, v[134:135]
	s_waitcnt vmcnt(16)
	v_pk_add_f32 v[62:63], v[62:63], v[66:67]
	v_pk_add_f32 v[60:61], v[60:61], v[64:65]
	v_pk_add_f32 v[58:59], v[58:59], v[70:71]
	v_pk_add_f32 v[56:57], v[56:57], v[68:69]
	v_pk_add_f32 v[42:43], v[42:43], v[74:75]
	v_pk_add_f32 v[40:41], v[40:41], v[72:73]
	v_pk_add_f32 v[34:35], v[34:35], v[78:79]
	v_pk_add_f32 v[32:33], v[32:33], v[76:77]
	v_pk_add_f32 v[54:55], v[54:55], v[82:83]
	v_pk_add_f32 v[52:53], v[52:53], v[80:81]
	v_pk_add_f32 v[50:51], v[50:51], v[86:87]
	v_pk_add_f32 v[48:49], v[48:49], v[84:85]
	v_pk_add_f32 v[26:27], v[26:27], v[90:91]
	v_pk_add_f32 v[24:25], v[24:25], v[88:89]
	v_pk_add_f32 v[22:23], v[22:23], v[94:95]
	v_pk_add_f32 v[20:21], v[20:21], v[92:93]
	v_pk_add_f32 v[46:47], v[46:47], v[98:99]
	v_pk_add_f32 v[44:45], v[44:45], v[96:97]
	v_pk_add_f32 v[38:39], v[38:39], v[102:103]
	v_pk_add_f32 v[36:37], v[36:37], v[100:101]
	v_pk_add_f32 v[14:15], v[14:15], v[106:107]
	v_pk_add_f32 v[12:13], v[12:13], v[104:105]
	v_pk_add_f32 v[10:11], v[10:11], v[110:111]
	v_pk_add_f32 v[8:9], v[8:9], v[108:109]
	v_pk_add_f32 v[30:31], v[30:31], v[114:115]
	v_pk_add_f32 v[28:29], v[28:29], v[112:113]
	v_pk_add_f32 v[18:19], v[18:19], v[118:119]
	v_pk_add_f32 v[16:17], v[16:17], v[116:117]
	v_pk_add_f32 v[6:7], v[6:7], v[122:123]
	v_pk_add_f32 v[4:5], v[4:5], v[120:121]
	v_pk_add_f32 v[2:3], v[2:3], v[126:127]
	v_pk_add_f32 v[0:1], v[0:1], v[124:125]
	global_store_dwordx4 v[136:137], v[60:63], off
	global_store_dwordx4 v[136:137], v[56:59], off offset:64
	global_store_dwordx4 v[136:137], v[40:43], off offset:512
	global_store_dwordx4 v[136:137], v[32:35], off offset:576
	global_store_dwordx4 v[142:143], v[52:55], off
	global_store_dwordx4 v[142:143], v[48:51], off offset:64
	global_store_dwordx4 v[142:143], v[24:27], off offset:512
	global_store_dwordx4 v[142:143], v[20:23], off offset:576
	global_store_dwordx4 v[144:145], v[44:47], off
	global_store_dwordx4 v[144:145], v[36:39], off offset:64
	global_store_dwordx4 v[144:145], v[12:15], off offset:512
	global_store_dwordx4 v[144:145], v[8:11], off offset:576
	global_store_dwordx4 v[134:135], v[28:31], off
	global_store_dwordx4 v[134:135], v[16:19], off offset:64
	global_store_dwordx4 v[134:135], v[4:7], off offset:512
	global_store_dwordx4 v[134:135], v[0:3], off offset:576
	s_and_b64 vcc, exec, s[6:7]
	s_mov_b32 s25, s4
	s_mov_b32 s26, s0
	s_mov_b64 s[14:15], s[10:11]
	s_mov_b64 s[12:13], s[8:9]
	s_cbranch_vccnz .Lal4_exit
	s_cmpk_gt_u32 s2, 0xff
	s_cbranch_scc0 .LBB0_1009
	s_barrier
	s_branch .LBB0_1009
